# phase-4 LoRA-input loop: loop-invariant rwkv_mu loads hoisted out of the loop (8 exposed L2 round trips per iteration removed)
# speedup vs baseline: 1.0083x; 1.0009x over previous
; __device__ __forceinline__ int ltid() { int t = (int)threadIdx.x; asm volatile("" : "+v"(t)); return t; }
; __device__ __forceinline__ void phase_prep(const Params& p, unsigned char* lds) {
;     const f16* Z = (const f16*)(p.ws + OFF_Z); u16* L = (u16*)(p.ws + OFF_L);
;     const int tid = ltid();
;     for (int idx = blockIdx.x * 512 + tid; idx < 16384 * 64; idx += gridDim.x * 512) {
;         const int m = idx >> 6, grp = idx & 63, t = m & 4095; u32x4 o = (u32x4){0u, 0u, 0u, 0u};
;         if (grp < 56) {
;             const int zc = 3072 + 8 * grp; const f16* zp = Z + (size_t)m * ZLD + zc;
;             const f16x8 z1 = *(const f16x8*)zp; f16x8 z0, z2;
;             if (t > 0) z0 = *(const f16x8*)(zp - ZLD); else { for (int j = 0; j < 8; ++j) z0[j] = (f16)0.f; }
;             if (t < 4095) z2 = *(const f16x8*)(zp + ZLD); else { for (int j = 0; j < 8; ++j) z2[j] = (f16)0.f; }
;             float v[8];
; #pragma unroll
;             for (int j = 0; j < 8; ++j) { const float a = (float)z1[j]; const float zs = a + (0.5f * ((float)z0[j] + (float)z2[j]) - a) * p.rwkv_mu[zc + j];
.LBB0_282:
	v_writelane_b32 v240, s69, 1
	s_or_b64 exec, exec, s[0:1]
	v_mov_b32_e32 v12, v170
	v_readlane_b32 s0, v240, 1
	s_waitcnt lgkmcnt(0)
	s_barrier
	s_add_u32 s82, s90, 0x1e160000
	s_addc_u32 s83, s91, 0
	v_add_u32_e32 v13, s0, v12
	s_mov_b32 s0, 0x100000
	v_cmp_gt_i32_e32 vcc, s0, v13
	s_and_saveexec_b64 s[8:9], vcc
	s_cbranch_execz .LBB0_371
	v_and_b32_e32 v4, 63, v12
	v_mov_b32_e32 v0, 0xc00
	v_lshl_or_b32 v2, v4, 3, v0
	v_readlane_b32 s44, v241, 2
	v_lshlrev_b32_e32 v0, 1, v2
	v_mov_b32_e32 v1, 0
	v_readlane_b32 s48, v241, 6
	v_readlane_b32 s49, v241, 7
	v_lshl_add_u64 v[14:15], s[96:97], 0, v[0:1]
	v_lshlrev_b32_e32 v0, 2, v2
	v_readlane_b32 s50, v241, 8
	v_readlane_b32 s51, v241, 9
	s_mov_b64 s[16:17], s[48:49]
	v_lshl_add_u64 v[16:17], s[16:17], 0, v[0:1]
	v_lshlrev_b32_e32 v0, 5, v4
	v_lshl_add_u64 v[2:3], s[16:17], 0, v[0:1]
	s_mov_b64 s[2:3], 0x3004
	v_lshl_add_u64 v[18:19], v[2:3], 0, s[2:3]
	s_mov_b64 s[2:3], 0x3008
	v_lshl_add_u64 v[20:21], v[2:3], 0, s[2:3]
	s_mov_b64 s[2:3], 0x300c
	v_lshl_add_u64 v[22:23], v[2:3], 0, s[2:3]
	s_mov_b64 s[2:3], 0x3010
	v_lshl_add_u64 v[24:25], v[2:3], 0, s[2:3]
	s_mov_b64 s[2:3], 0x3014
	v_lshl_add_u64 v[26:27], v[2:3], 0, s[2:3]
	s_mov_b64 s[2:3], 0x3018
	v_lshl_add_u64 v[28:29], v[2:3], 0, s[2:3]
	s_mov_b64 s[2:3], 0x301c
	v_lshlrev_b32_e32 v0, 4, v4
	v_cmp_gt_u32_e64 s[0:1], 56, v4
	v_cmp_lt_u32_e64 s[6:7], 11, v4
	v_cmp_lt_u32_e64 s[4:5], 23, v4
	v_lshl_add_u64 v[30:31], v[2:3], 0, s[2:3]
	v_lshl_add_u64 v[32:33], s[82:83], 0, v[0:1]
	s_mov_b64 s[10:11], 0
	s_movk_i32 s2, 0xfff
	s_movk_i32 s3, 0x3400
	s_mov_b32 s30, 0.5
	s_mov_b32 s31, 0x3f200000
	s_mov_b32 s38, 0x3fb8aa3b
	s_mov_b32 s39, 0xc2ce8ed0
	s_mov_b32 s41, 0x42b17218
	v_mov_b32_e32 v38, 0x3ca908c9
	s_brev_b32 s42, -2
	s_mov_b32 s43, 0xfffff
	v_mov_b32_e32 v39, 0x7f800000
	v_readlane_b32 s45, v241, 3
	v_readlane_b32 s46, v241, 4
	v_readlane_b32 s47, v241, 5
	v_readlane_b32 s52, v241, 10
	v_readlane_b32 s53, v241, 11
	v_readlane_b32 s54, v241, 12
	v_readlane_b32 s55, v241, 13
	v_readlane_b32 s56, v241, 14
	v_readlane_b32 s57, v241, 15
	v_readlane_b32 s58, v241, 16
	v_readlane_b32 s59, v241, 17
	s_mov_b64 s[18:19], s[50:51]
	s_mov_b64 s[16:17], exec
	s_and_b64 exec, exec, s[0:1]
	global_load_dword v100, v[16:17], off
	global_load_dword v101, v[18:19], off
	global_load_dword v102, v[20:21], off
	global_load_dword v103, v[22:23], off
	global_load_dword v104, v[24:25], off
	global_load_dword v105, v[26:27], off
	global_load_dword v106, v[28:29], off
	global_load_dword v107, v[30:31], off
	s_mov_b64 exec, s[16:17]
	s_waitcnt vmcnt(0)
	s_branch .LBB0_287

; __device__ __forceinline__ float sigmoidf_(float x) { return 1.0f / (1.0f + __expf(-x)); }
; __device__ __forceinline__ void phase_prep(const Params& p, unsigned char* lds) {
;     ...
;             for (int j = 0; j < 8; ++j) { const float a = (float)z1[j]; const float zs = a + (0.5f * ((float)z0[j] + (float)z2[j]) - a) * p.rwkv_mu[zc + j];
;                 v[j] = grp < 12 ? tanhf(zs) : (grp < 24 ? zs : sigmoidf_(zs)); }
.LBB0_292:
	s_or_b64 exec, exec, s[16:17]
	v_mov_b32_e32 v36, v100
	s_waitcnt vmcnt(0)
	v_cvt_f32_f16_e32 v37, v8
	v_cvt_f32_f16_e32 v40, v4
	v_add_f32_e32 v37, v37, v40
	v_fma_mix_f32 v37, v37, s30, -v0 op_sel_hi:[0,0,1]
	s_waitcnt vmcnt(0)
	v_fma_mix_f32 v36, v36, v37, v0 op_sel_hi:[0,0,1]
	s_and_saveexec_b64 s[16:17], s[6:7]
	s_xor_b64 s[16:17], exec, s[16:17]
	s_cbranch_execz .LBB0_296
	s_and_saveexec_b64 s[28:29], s[4:5]
	s_cbranch_execz .LBB0_295
	v_mul_f32_e32 v36, 0xbfb8aa3b, v36
	v_exp_f32_e32 v36, v36
	s_nop 0
	v_add_f32_e32 v36, 1.0, v36
	v_rcp_f32_e32 v40, v36
	s_nop 0
	v_fma_f32 v42, -v36, v40, 1.0
	v_fma_f32 v37, v42, v40, v40
	v_div_fixup_f32 v36, v37, v36, 1.0

; __device__ __forceinline__ float sigmoidf_(float x) { return 1.0f / (1.0f + __expf(-x)); }
; __device__ __forceinline__ void phase_prep(const Params& p, unsigned char* lds) {
;     ...
;             for (int j = 0; j < 8; ++j) { const float a = (float)z1[j]; const float zs = a + (0.5f * ((float)z0[j] + (float)z2[j]) - a) * p.rwkv_mu[zc + j];
;                 v[j] = grp < 12 ? tanhf(zs) : (grp < 24 ? zs : sigmoidf_(zs)); }
.LBB0_302:
	s_or_b64 exec, exec, s[16:17]
	v_mov_b32_e32 v37, v101
	v_cvt_f32_f16_sdwa v8, v8 dst_sel:DWORD dst_unused:UNUSED_PAD src0_sel:WORD_1
	v_cvt_f32_f16_sdwa v4, v4 dst_sel:DWORD dst_unused:UNUSED_PAD src0_sel:WORD_1
	v_add_f32_e32 v4, v8, v4
	v_fma_mix_f32 v4, v4, s30, -v0 op_sel:[0,0,1] op_sel_hi:[0,0,1]
	s_waitcnt vmcnt(0)
	v_fma_mix_f32 v0, v4, v37, v0 op_sel:[0,0,1] op_sel_hi:[0,0,1]
	s_and_saveexec_b64 s[16:17], s[6:7]
	s_xor_b64 s[16:17], exec, s[16:17]
	s_cbranch_execz .LBB0_306
	s_and_saveexec_b64 s[28:29], s[4:5]
	s_cbranch_execz .LBB0_305
	v_mul_f32_e32 v0, 0xbfb8aa3b, v0
	v_exp_f32_e32 v0, v0
	s_nop 0
	v_add_f32_e32 v0, 1.0, v0
	v_rcp_f32_e32 v8, v0
	s_nop 0
	v_fma_f32 v40, -v0, v8, 1.0
	v_fma_f32 v4, v40, v8, v8
	v_div_fixup_f32 v0, v4, v0, 1.0

; __device__ __forceinline__ float sigmoidf_(float x) { return 1.0f / (1.0f + __expf(-x)); }
; __device__ __forceinline__ void phase_prep(const Params& p, unsigned char* lds) {
;     ...
;             for (int j = 0; j < 8; ++j) { const float a = (float)z1[j]; const float zs = a + (0.5f * ((float)z0[j] + (float)z2[j]) - a) * p.rwkv_mu[zc + j];
;                 v[j] = grp < 12 ? tanhf(zs) : (grp < 24 ? zs : sigmoidf_(zs)); }
.LBB0_312:
	s_or_b64 exec, exec, s[16:17]
	v_mov_b32_e32 v4, v102
	v_cvt_f32_f16_e32 v8, v9
	v_cvt_f32_f16_e32 v37, v5
	v_add_f32_e32 v8, v8, v37
	v_fma_mix_f32 v8, v8, s30, -v1 op_sel_hi:[0,0,1]
	s_waitcnt vmcnt(0)
	v_fma_mix_f32 v4, v8, v4, v1 op_sel_hi:[0,0,1]
	s_and_saveexec_b64 s[16:17], s[6:7]
	s_xor_b64 s[16:17], exec, s[16:17]
	s_cbranch_execz .LBB0_316
	s_and_saveexec_b64 s[28:29], s[4:5]
	s_cbranch_execz .LBB0_315
	v_mul_f32_e32 v4, 0xbfb8aa3b, v4
	v_exp_f32_e32 v4, v4
	s_nop 0
	v_add_f32_e32 v4, 1.0, v4
	v_rcp_f32_e32 v37, v4
	s_nop 0
	v_fma_f32 v41, -v4, v37, 1.0
	v_fma_f32 v8, v41, v37, v37
	v_div_fixup_f32 v4, v8, v4, 1.0

; __device__ __forceinline__ float sigmoidf_(float x) { return 1.0f / (1.0f + __expf(-x)); }
; __device__ __forceinline__ void phase_prep(const Params& p, unsigned char* lds) {
;     ...
;             for (int j = 0; j < 8; ++j) { const float a = (float)z1[j]; const float zs = a + (0.5f * ((float)z0[j] + (float)z2[j]) - a) * p.rwkv_mu[zc + j];
;                 v[j] = grp < 12 ? tanhf(zs) : (grp < 24 ? zs : sigmoidf_(zs)); }
.LBB0_322:
	s_or_b64 exec, exec, s[16:17]
	v_mov_b32_e32 v8, v103
	v_cvt_f32_f16_sdwa v9, v9 dst_sel:DWORD dst_unused:UNUSED_PAD src0_sel:WORD_1
	v_cvt_f32_f16_sdwa v5, v5 dst_sel:DWORD dst_unused:UNUSED_PAD src0_sel:WORD_1
	v_add_f32_e32 v5, v9, v5
	v_fma_mix_f32 v5, v5, s30, -v1 op_sel:[0,0,1] op_sel_hi:[0,0,1]
	s_waitcnt vmcnt(0)
	v_fma_mix_f32 v1, v5, v8, v1 op_sel:[0,0,1] op_sel_hi:[0,0,1]
	s_and_saveexec_b64 s[16:17], s[6:7]
	s_xor_b64 s[16:17], exec, s[16:17]
	s_cbranch_execz .LBB0_326
	s_and_saveexec_b64 s[28:29], s[4:5]
	s_cbranch_execz .LBB0_325
	v_mul_f32_e32 v1, 0xbfb8aa3b, v1
	v_exp_f32_e32 v1, v1
	s_nop 0
	v_add_f32_e32 v1, 1.0, v1
	v_rcp_f32_e32 v8, v1
	s_nop 0
	v_fma_f32 v37, -v1, v8, 1.0
	v_fma_f32 v5, v37, v8, v8
	v_div_fixup_f32 v1, v5, v1, 1.0

; __device__ __forceinline__ float sigmoidf_(float x) { return 1.0f / (1.0f + __expf(-x)); }
; __device__ __forceinline__ void phase_prep(const Params& p, unsigned char* lds) {
;     ...
;             for (int j = 0; j < 8; ++j) { const float a = (float)z1[j]; const float zs = a + (0.5f * ((float)z0[j] + (float)z2[j]) - a) * p.rwkv_mu[zc + j];
;                 v[j] = grp < 12 ? tanhf(zs) : (grp < 24 ? zs : sigmoidf_(zs)); }
.LBB0_332:
	s_or_b64 exec, exec, s[16:17]
	v_mov_b32_e32 v5, v104
	v_cvt_f32_f16_e32 v8, v10
	v_cvt_f32_f16_e32 v9, v6
	v_add_f32_e32 v8, v8, v9
	v_fma_mix_f32 v8, v8, s30, -v2 op_sel_hi:[0,0,1]
	s_waitcnt vmcnt(0)
	v_fma_mix_f32 v5, v8, v5, v2 op_sel_hi:[0,0,1]
	s_and_saveexec_b64 s[16:17], s[6:7]
	s_xor_b64 s[16:17], exec, s[16:17]
	s_cbranch_execz .LBB0_336
	s_and_saveexec_b64 s[28:29], s[4:5]
	s_cbranch_execz .LBB0_335
	v_mul_f32_e32 v5, 0xbfb8aa3b, v5
	v_exp_f32_e32 v5, v5
	s_nop 0
	v_add_f32_e32 v5, 1.0, v5
	v_rcp_f32_e32 v9, v5
	s_nop 0
	v_fma_f32 v40, -v5, v9, 1.0
	v_fma_f32 v8, v40, v9, v9
	v_div_fixup_f32 v5, v8, v5, 1.0

; __device__ __forceinline__ float sigmoidf_(float x) { return 1.0f / (1.0f + __expf(-x)); }
; __device__ __forceinline__ void phase_prep(const Params& p, unsigned char* lds) {
;     ...
;             for (int j = 0; j < 8; ++j) { const float a = (float)z1[j]; const float zs = a + (0.5f * ((float)z0[j] + (float)z2[j]) - a) * p.rwkv_mu[zc + j];
;                 v[j] = grp < 12 ? tanhf(zs) : (grp < 24 ? zs : sigmoidf_(zs)); }
.LBB0_342:
	s_or_b64 exec, exec, s[16:17]
	v_mov_b32_e32 v8, v105
	v_cvt_f32_f16_sdwa v9, v10 dst_sel:DWORD dst_unused:UNUSED_PAD src0_sel:WORD_1
	v_cvt_f32_f16_sdwa v6, v6 dst_sel:DWORD dst_unused:UNUSED_PAD src0_sel:WORD_1
	v_add_f32_e32 v6, v9, v6
	v_fma_mix_f32 v6, v6, s30, -v2 op_sel:[0,0,1] op_sel_hi:[0,0,1]
	s_waitcnt vmcnt(0)
	v_fma_mix_f32 v2, v6, v8, v2 op_sel:[0,0,1] op_sel_hi:[0,0,1]
	s_and_saveexec_b64 s[16:17], s[6:7]
	s_xor_b64 s[16:17], exec, s[16:17]
	s_cbranch_execz .LBB0_346
	s_and_saveexec_b64 s[28:29], s[4:5]
	s_cbranch_execz .LBB0_345
	v_mul_f32_e32 v2, 0xbfb8aa3b, v2
	v_exp_f32_e32 v2, v2
	s_nop 0
	v_add_f32_e32 v2, 1.0, v2
	v_rcp_f32_e32 v8, v2
	s_nop 0
	v_fma_f32 v10, -v2, v8, 1.0
	v_fma_f32 v6, v10, v8, v8
	v_div_fixup_f32 v2, v6, v2, 1.0

; __device__ __forceinline__ float sigmoidf_(float x) { return 1.0f / (1.0f + __expf(-x)); }
; __device__ __forceinline__ void phase_prep(const Params& p, unsigned char* lds) {
;     ...
;             for (int j = 0; j < 8; ++j) { const float a = (float)z1[j]; const float zs = a + (0.5f * ((float)z0[j] + (float)z2[j]) - a) * p.rwkv_mu[zc + j];
;                 v[j] = grp < 12 ? tanhf(zs) : (grp < 24 ? zs : sigmoidf_(zs)); }
.LBB0_352:
	s_or_b64 exec, exec, s[16:17]
	v_mov_b32_e32 v6, v106
	v_cvt_f32_f16_e32 v8, v11
	v_cvt_f32_f16_e32 v9, v7
	v_add_f32_e32 v8, v8, v9
	v_fma_mix_f32 v8, v8, s30, -v3 op_sel_hi:[0,0,1]
	s_waitcnt vmcnt(0)
	v_fma_mix_f32 v6, v8, v6, v3 op_sel_hi:[0,0,1]
	s_and_saveexec_b64 s[16:17], s[6:7]
	s_xor_b64 s[16:17], exec, s[16:17]
	s_cbranch_execz .LBB0_356
	s_and_saveexec_b64 s[28:29], s[4:5]
	s_cbranch_execz .LBB0_355
	v_mul_f32_e32 v6, 0xbfb8aa3b, v6
	v_exp_f32_e32 v6, v6
	s_nop 0
	v_add_f32_e32 v6, 1.0, v6
	v_rcp_f32_e32 v9, v6
	s_nop 0
	v_fma_f32 v37, -v6, v9, 1.0
	v_fma_f32 v8, v37, v9, v9
	v_div_fixup_f32 v6, v8, v6, 1.0

; __device__ __forceinline__ float sigmoidf_(float x) { return 1.0f / (1.0f + __expf(-x)); }
; __device__ __forceinline__ void phase_prep(const Params& p, unsigned char* lds) {
;     ...
;             for (int j = 0; j < 8; ++j) { const float a = (float)z1[j]; const float zs = a + (0.5f * ((float)z0[j] + (float)z2[j]) - a) * p.rwkv_mu[zc + j];
;                 v[j] = grp < 12 ? tanhf(zs) : (grp < 24 ? zs : sigmoidf_(zs)); }
.LBB0_362:
	s_or_b64 exec, exec, s[16:17]
	v_mov_b32_e32 v8, v107
	v_cvt_f32_f16_sdwa v9, v11 dst_sel:DWORD dst_unused:UNUSED_PAD src0_sel:WORD_1
	v_cvt_f32_f16_sdwa v7, v7 dst_sel:DWORD dst_unused:UNUSED_PAD src0_sel:WORD_1
	v_add_f32_e32 v7, v9, v7
	v_fma_mix_f32 v7, v7, s30, -v3 op_sel:[0,0,1] op_sel_hi:[0,0,1]
	s_waitcnt vmcnt(0)
	v_fma_mix_f32 v3, v7, v8, v3 op_sel:[0,0,1] op_sel_hi:[0,0,1]
	s_and_saveexec_b64 s[16:17], s[6:7]
	s_xor_b64 s[16:17], exec, s[16:17]
	s_cbranch_execz .LBB0_366
	s_and_saveexec_b64 s[28:29], s[4:5]
	s_cbranch_execz .LBB0_365
	v_mul_f32_e32 v3, 0xbfb8aa3b, v3
	v_exp_f32_e32 v3, v3
	s_nop 0
	v_add_f32_e32 v3, 1.0, v3
	v_rcp_f32_e32 v8, v3
	s_nop 0
	v_fma_f32 v10, -v3, v8, 1.0
	v_fma_f32 v7, v10, v8, v8
	v_div_fixup_f32 v3, v7, v3, 1.0
